# plain-GEMM epilogue: row-scale loads hoisted into one batch, per-section store waits removed
# baseline (speedup 1.0000x reference)
.LBB0_419:
	v_lshlrev_b32_e32 v132, 8, v132
	v_mov_b32_e32 v154, v174
	v_add_u32_e32 v132, s70, v132
	v_cndmask_b32_e64 v152, 0, 1, s[46:47]
	v_and_or_b32 v150, v154, 15, v132
	v_ashrrev_i32_e32 v151, 31, v150
	v_mov_b32_e32 v132, 1.0
	v_cmp_ne_u32_e64 s[42:43], 1, v152
	s_andn2_b64 vcc, exec, s[46:47]
	v_lshl_add_u64 v[152:153], v[150:151], 2, s[36:37]
	v_mov_b32_e32 v156, 1.0
	v_mov_b32_e32 v208, 1.0
	v_mov_b32_e32 v210, 1.0
	v_mov_b32_e32 v212, 1.0
	v_mov_b32_e32 v214, 1.0
	v_mov_b32_e32 v216, 1.0
	v_mov_b32_e32 v218, 1.0
	v_mov_b32_e32 v220, 1.0
	v_mov_b32_e32 v222, 1.0
	s_cbranch_vccnz .LBB0_421
	global_load_dword v208, v[152:153], off
	global_load_dword v210, v[152:153], off offset:64
	global_load_dword v212, v[152:153], off offset:128
	global_load_dword v214, v[152:153], off offset:192
	global_load_dword v216, v[152:153], off offset:512
	global_load_dword v218, v[152:153], off offset:576
	global_load_dword v220, v[152:153], off offset:640
	global_load_dword v222, v[152:153], off offset:704
	s_waitcnt vmcnt(0)
.LBB0_421:
	v_lshlrev_b32_e32 v151, 8, v163
	v_ashrrev_i32_e32 v154, 1, v154
	v_or_b32_e32 v151, s71, v151
	v_and_b32_e32 v154, -8, v154
	v_add_u32_e32 v154, v151, v154
	v_mad_i64_i32 v[158:159], s[8:9], v150, s22, 0
	v_ashrrev_i32_e32 v155, 31, v154
	v_lshl_add_u64 v[158:159], v[158:159], 1, s[4:5]
	v_lshl_add_u64 v[158:159], v[154:155], 1, v[158:159]
	v_pk_mul_f32 v[130:131], v[130:131], v[208:209] op_sel_hi:[1,0]
	v_pk_mul_f32 v[128:129], v[128:129], v[208:209] op_sel_hi:[1,0]
	v_pk_mul_f32 v[164:165], v[126:127], v[208:209] op_sel_hi:[1,0]
	v_pk_mul_f32 v[126:127], v[124:125], v[208:209] op_sel_hi:[1,0]
	v_cvt_pk_bf16_f32 v124, v128, v129
	v_cvt_pk_bf16_f32 v125, v130, v131
	s_and_b64 vcc, exec, s[42:43]
	v_cvt_pk_bf16_f32 v126, v126, v127
	v_cvt_pk_bf16_f32 v127, v164, v165
	global_store_dwordx4 v[158:159], v[124:127], off
	v_pk_mul_f32 v[122:123], v[122:123], v[208:209] op_sel_hi:[1,0]
	v_pk_mul_f32 v[120:121], v[120:121], v[208:209] op_sel_hi:[1,0]
	v_pk_mul_f32 v[124:125], v[118:119], v[208:209] op_sel_hi:[1,0]
	v_pk_mul_f32 v[118:119], v[116:117], v[208:209] op_sel_hi:[1,0]
	v_cvt_pk_bf16_f32 v116, v120, v121
	v_cvt_pk_bf16_f32 v117, v122, v123
	s_nop 0
	v_cvt_pk_bf16_f32 v118, v118, v119
	v_cvt_pk_bf16_f32 v119, v124, v125
	global_store_dwordx4 v[158:159], v[116:119], off offset:256
	s_nop 0
.LBB0_423:
	s_nop 0
	v_or_b32_e32 v116, 16, v150
	v_mad_i64_i32 v[116:117], s[8:9], v116, s22, 0
	v_lshl_add_u64 v[116:117], v[116:117], 1, s[4:5]
	v_lshl_add_u64 v[116:117], v[154:155], 1, v[116:117]
	v_pk_mul_f32 v[114:115], v[114:115], v[210:211] op_sel_hi:[1,0]
	v_pk_mul_f32 v[112:113], v[112:113], v[210:211] op_sel_hi:[1,0]
	v_pk_mul_f32 v[118:119], v[110:111], v[210:211] op_sel_hi:[1,0]
	v_pk_mul_f32 v[110:111], v[108:109], v[210:211] op_sel_hi:[1,0]
	v_cvt_pk_bf16_f32 v108, v112, v113
	v_cvt_pk_bf16_f32 v109, v114, v115
	v_pk_mul_f32 v[106:107], v[106:107], v[210:211] op_sel_hi:[1,0]
	v_cvt_pk_bf16_f32 v110, v110, v111
	v_cvt_pk_bf16_f32 v111, v118, v119
	global_store_dwordx4 v[116:117], v[108:111], off
	v_pk_mul_f32 v[104:105], v[104:105], v[210:211] op_sel_hi:[1,0]
	s_and_b64 vcc, exec, s[42:43]
	v_pk_mul_f32 v[108:109], v[102:103], v[210:211] op_sel_hi:[1,0]
	v_pk_mul_f32 v[102:103], v[100:101], v[210:211] op_sel_hi:[1,0]
	v_cvt_pk_bf16_f32 v100, v104, v105
	v_cvt_pk_bf16_f32 v101, v106, v107
	s_nop 0
	v_cvt_pk_bf16_f32 v102, v102, v103
	v_cvt_pk_bf16_f32 v103, v108, v109
	global_store_dwordx4 v[116:117], v[100:103], off offset:256
	s_nop 1
	v_mov_b32_e32 v100, 1.0
	v_mov_b32_e32 v102, 1.0
	s_nop 0
.LBB0_425:
	v_or_b32_e32 v101, 32, v150
	v_mad_i64_i32 v[104:105], s[8:9], v101, s22, 0
	v_lshl_add_u64 v[104:105], v[104:105], 1, s[4:5]
	v_lshl_add_u64 v[104:105], v[154:155], 1, v[104:105]
	v_pk_mul_f32 v[98:99], v[98:99], v[212:213] op_sel_hi:[1,0]
	v_pk_mul_f32 v[96:97], v[96:97], v[212:213] op_sel_hi:[1,0]
	v_pk_mul_f32 v[106:107], v[94:95], v[212:213] op_sel_hi:[1,0]
	v_pk_mul_f32 v[94:95], v[92:93], v[212:213] op_sel_hi:[1,0]
	v_cvt_pk_bf16_f32 v92, v96, v97
	v_cvt_pk_bf16_f32 v93, v98, v99
	s_and_b64 vcc, exec, s[42:43]
	v_cvt_pk_bf16_f32 v94, v94, v95
	v_cvt_pk_bf16_f32 v95, v106, v107
	global_store_dwordx4 v[104:105], v[92:95], off
	v_pk_mul_f32 v[90:91], v[90:91], v[212:213] op_sel_hi:[1,0]
	v_pk_mul_f32 v[88:89], v[88:89], v[212:213] op_sel_hi:[1,0]
	v_pk_mul_f32 v[92:93], v[86:87], v[212:213] op_sel_hi:[1,0]
	v_pk_mul_f32 v[86:87], v[84:85], v[212:213] op_sel_hi:[1,0]
	v_cvt_pk_bf16_f32 v84, v88, v89
	v_cvt_pk_bf16_f32 v85, v90, v91
	s_nop 0
	v_cvt_pk_bf16_f32 v86, v86, v87
	v_cvt_pk_bf16_f32 v87, v92, v93
	global_store_dwordx4 v[104:105], v[84:87], off offset:256
	s_nop 0
.LBB0_427:
	s_nop 0
	v_or_b32_e32 v84, 48, v150
	v_mad_i64_i32 v[84:85], s[8:9], v84, s22, 0
	v_lshl_add_u64 v[84:85], v[84:85], 1, s[4:5]
	v_lshl_add_u64 v[84:85], v[154:155], 1, v[84:85]
	v_pk_mul_f32 v[82:83], v[82:83], v[214:215] op_sel_hi:[1,0]
	v_pk_mul_f32 v[80:81], v[80:81], v[214:215] op_sel_hi:[1,0]
	v_pk_mul_f32 v[86:87], v[78:79], v[214:215] op_sel_hi:[1,0]
	v_pk_mul_f32 v[78:79], v[76:77], v[214:215] op_sel_hi:[1,0]
	v_cvt_pk_bf16_f32 v76, v80, v81
	v_cvt_pk_bf16_f32 v77, v82, v83
	v_pk_mul_f32 v[74:75], v[74:75], v[214:215] op_sel_hi:[1,0]
	v_cvt_pk_bf16_f32 v78, v78, v79
	v_cvt_pk_bf16_f32 v79, v86, v87
	global_store_dwordx4 v[84:85], v[76:79], off
	v_pk_mul_f32 v[72:73], v[72:73], v[214:215] op_sel_hi:[1,0]
	s_and_b64 vcc, exec, s[42:43]
	v_pk_mul_f32 v[76:77], v[70:71], v[214:215] op_sel_hi:[1,0]
	v_pk_mul_f32 v[70:71], v[68:69], v[214:215] op_sel_hi:[1,0]
	v_cvt_pk_bf16_f32 v68, v72, v73
	v_cvt_pk_bf16_f32 v69, v74, v75
	s_nop 0
	v_cvt_pk_bf16_f32 v70, v70, v71
	v_cvt_pk_bf16_f32 v71, v76, v77
	global_store_dwordx4 v[84:85], v[68:71], off offset:256
	s_nop 1
	v_mov_b32_e32 v68, 1.0
	v_mov_b32_e32 v70, 1.0
	s_nop 0
.LBB0_429:
	v_add_u32_e32 v69, 0x80, v150
	v_mad_i64_i32 v[72:73], s[8:9], v69, s22, 0
	v_lshl_add_u64 v[72:73], v[72:73], 1, s[4:5]
	v_lshl_add_u64 v[72:73], v[154:155], 1, v[72:73]
	v_pk_mul_f32 v[66:67], v[66:67], v[216:217] op_sel_hi:[1,0]
	v_pk_mul_f32 v[64:65], v[64:65], v[216:217] op_sel_hi:[1,0]
	v_pk_mul_f32 v[74:75], v[62:63], v[216:217] op_sel_hi:[1,0]
	v_pk_mul_f32 v[62:63], v[60:61], v[216:217] op_sel_hi:[1,0]
	v_cvt_pk_bf16_f32 v60, v64, v65
	v_cvt_pk_bf16_f32 v61, v66, v67
	s_and_b64 vcc, exec, s[42:43]
	v_cvt_pk_bf16_f32 v62, v62, v63
	v_cvt_pk_bf16_f32 v63, v74, v75
	global_store_dwordx4 v[72:73], v[60:63], off
	v_pk_mul_f32 v[58:59], v[58:59], v[216:217] op_sel_hi:[1,0]
	v_pk_mul_f32 v[56:57], v[56:57], v[216:217] op_sel_hi:[1,0]
	v_pk_mul_f32 v[60:61], v[54:55], v[216:217] op_sel_hi:[1,0]
	v_pk_mul_f32 v[54:55], v[52:53], v[216:217] op_sel_hi:[1,0]
	v_cvt_pk_bf16_f32 v52, v56, v57
	v_cvt_pk_bf16_f32 v53, v58, v59
	s_nop 0
	v_cvt_pk_bf16_f32 v54, v54, v55
	v_cvt_pk_bf16_f32 v55, v60, v61
	global_store_dwordx4 v[72:73], v[52:55], off offset:256
	s_nop 0
.LBB0_431:
	s_nop 0
	v_add_u32_e32 v52, 0x90, v150
	v_mad_i64_i32 v[52:53], s[8:9], v52, s22, 0
	v_lshl_add_u64 v[52:53], v[52:53], 1, s[4:5]
	v_lshl_add_u64 v[52:53], v[154:155], 1, v[52:53]
	v_pk_mul_f32 v[50:51], v[50:51], v[218:219] op_sel_hi:[1,0]
	v_pk_mul_f32 v[48:49], v[48:49], v[218:219] op_sel_hi:[1,0]
	v_pk_mul_f32 v[54:55], v[46:47], v[218:219] op_sel_hi:[1,0]
	v_pk_mul_f32 v[46:47], v[44:45], v[218:219] op_sel_hi:[1,0]
	v_cvt_pk_bf16_f32 v44, v48, v49
	v_cvt_pk_bf16_f32 v45, v50, v51
	v_pk_mul_f32 v[42:43], v[42:43], v[218:219] op_sel_hi:[1,0]
	v_cvt_pk_bf16_f32 v46, v46, v47
	v_cvt_pk_bf16_f32 v47, v54, v55
	global_store_dwordx4 v[52:53], v[44:47], off
	v_pk_mul_f32 v[40:41], v[40:41], v[218:219] op_sel_hi:[1,0]
	s_and_b64 vcc, exec, s[42:43]
	v_pk_mul_f32 v[44:45], v[38:39], v[218:219] op_sel_hi:[1,0]
	v_pk_mul_f32 v[38:39], v[36:37], v[218:219] op_sel_hi:[1,0]
	v_cvt_pk_bf16_f32 v36, v40, v41
	v_cvt_pk_bf16_f32 v37, v42, v43
	s_nop 0
	v_cvt_pk_bf16_f32 v38, v38, v39
	v_cvt_pk_bf16_f32 v39, v44, v45
	global_store_dwordx4 v[52:53], v[36:39], off offset:256
	s_nop 1
	v_mov_b32_e32 v36, 1.0
	v_mov_b32_e32 v38, 1.0
	s_nop 0
.LBB0_433:
	v_add_u32_e32 v37, 0xa0, v150
	v_mad_i64_i32 v[40:41], s[8:9], v37, s22, 0
	v_lshl_add_u64 v[40:41], v[40:41], 1, s[4:5]
	v_lshl_add_u64 v[40:41], v[154:155], 1, v[40:41]
	v_pk_mul_f32 v[34:35], v[34:35], v[220:221] op_sel_hi:[1,0]
	v_pk_mul_f32 v[32:33], v[32:33], v[220:221] op_sel_hi:[1,0]
	v_pk_mul_f32 v[42:43], v[30:31], v[220:221] op_sel_hi:[1,0]
	v_pk_mul_f32 v[30:31], v[28:29], v[220:221] op_sel_hi:[1,0]
	v_cvt_pk_bf16_f32 v28, v32, v33
	v_cvt_pk_bf16_f32 v29, v34, v35
	s_and_b64 vcc, exec, s[42:43]
	v_cvt_pk_bf16_f32 v30, v30, v31
	v_cvt_pk_bf16_f32 v31, v42, v43
	global_store_dwordx4 v[40:41], v[28:31], off
	v_pk_mul_f32 v[26:27], v[26:27], v[220:221] op_sel_hi:[1,0]
	v_pk_mul_f32 v[24:25], v[24:25], v[220:221] op_sel_hi:[1,0]
	v_pk_mul_f32 v[28:29], v[22:23], v[220:221] op_sel_hi:[1,0]
	v_pk_mul_f32 v[22:23], v[20:21], v[220:221] op_sel_hi:[1,0]
	v_cvt_pk_bf16_f32 v20, v24, v25
	v_cvt_pk_bf16_f32 v21, v26, v27
	s_nop 0
	v_cvt_pk_bf16_f32 v22, v22, v23
	v_cvt_pk_bf16_f32 v23, v28, v29
	global_store_dwordx4 v[40:41], v[20:23], off offset:256
	s_nop 0
.LBB0_435:
	s_nop 0
	v_add_u32_e32 v20, 0xb0, v150
	v_mad_i64_i32 v[20:21], s[8:9], v20, s22, 0
	v_lshl_add_u64 v[20:21], v[20:21], 1, s[4:5]
	v_lshl_add_u64 v[20:21], v[154:155], 1, v[20:21]
	v_pk_mul_f32 v[18:19], v[18:19], v[222:223] op_sel_hi:[1,0]
	v_pk_mul_f32 v[16:17], v[16:17], v[222:223] op_sel_hi:[1,0]
	v_pk_mul_f32 v[22:23], v[14:15], v[222:223] op_sel_hi:[1,0]
	v_pk_mul_f32 v[14:15], v[12:13], v[222:223] op_sel_hi:[1,0]
	v_cvt_pk_bf16_f32 v12, v16, v17
	v_cvt_pk_bf16_f32 v13, v18, v19
	s_and_b64 vcc, exec, s[40:41]
	v_cvt_pk_bf16_f32 v14, v14, v15
	v_cvt_pk_bf16_f32 v15, v22, v23
	global_store_dwordx4 v[20:21], v[12:15], off
	s_mov_b64 s[40:41], -1
	v_pk_mul_f32 v[10:11], v[10:11], v[222:223] op_sel_hi:[1,0]
	v_pk_mul_f32 v[12:13], v[6:7], v[222:223] op_sel_hi:[1,0]
	v_pk_mul_f32 v[6:7], v[4:5], v[222:223] op_sel_hi:[1,0]
	v_pk_mul_f32 v[8:9], v[8:9], v[222:223] op_sel_hi:[1,0]
	s_nop 0
	v_cvt_pk_bf16_f32 v4, v8, v9
	v_cvt_pk_bf16_f32 v5, v10, v11
	v_cvt_pk_bf16_f32 v6, v6, v7
	v_cvt_pk_bf16_f32 v7, v12, v13
	global_store_dwordx4 v[20:21], v[4:7], off offset:256
	s_cbranch_vccnz .LBB0_408
	s_and_b64 vcc, exec, s[38:39]
	s_cbranch_vccnz .LBB0_407
	s_barrier
	s_branch .LBB0_407
